# v46 + NSA flush read-modify-write: the 8 serialized loads of each FX-path flush issued together up front (counted vmcnt waits)
# speedup vs baseline: 1.0048x; 1.0048x over previous
; DI float bf2f(bf16_t h) { return __uint_as_float(((unsigned)h) << 16); }
; DI float bflo(unsigned u) { return __uint_as_float(u << 16); }
; DI float bfhi(unsigned u) { return __uint_as_float(u & 0xffff0000u); }
; DI float sigmoidf(float x) { return __builtin_amdgcn_rcpf(1.f + __expf(-x)); }
; template <bool FIRST>
; DI void nsa_flush(const int quad, bf16_t* optr, const AttnSt& st, const float (&sc)[2]) {
; #pragma unroll
;   for (int h = 0; h < 2; ++h)
; #pragma unroll
;     for (int dt = 0; dt < 4; ++dt) {
;       uint2* q = (uint2*)(optr + h * 64 + dt * 16 + quad * 4);
;       f32x4 o = st.O[h][dt] * sc[h];
;       if (!FIRST) {
;         uint2 pv = *q;
;         o[0] += bflo(pv.x); o[1] += bfhi(pv.x); o[2] += bflo(pv.y); o[3] += bfhi(pv.y);
;       }
;       uint2 u;
;       u.x = pack2(o[0], o[1]);
;       u.y = pack2(o[2], o[3]);
;       *q = u;
;     }
; }
; template <bool FX>
; DI void nsa_tile(const Params& p, int b, int g, int tile, bf16_t* lds, const float CL) {
;     ...
;     {
;       float sc[2];
; #pragma unroll
;       for (int h = 0; h < 2; ++h) {
;         float l;
;         if (FX) {
;           l = st.L[h][0];
;         } else {
;           l = st.l[h];
;           l += shx(l, 16, lane);
;           l += shx(l, 32, lane);
;         }
;         sc[h] = (l > 0.f) ? sigmoidf(bf2f(ztok[C_GT + 1 * 8 + g * 4 + hp * 2 + h])) / l : 0.f;
;       }
;       nsa_flush<false>(quad, otok + hp * 128, st, sc);
;     }
.LBB0_679:
	s_or_b64 exec, exec, s[2:3]
	s_lshl_b32 s28, s7, 1
	v_lshl_add_u64 v[158:159], v[128:129], 0, s[28:29]
	global_load_dwordx2 v[220:221], v[158:159], off
	global_load_dwordx2 v[222:223], v[158:159], off offset:32
	global_load_dwordx2 v[224:225], v[158:159], off offset:64
	global_load_dwordx2 v[226:227], v[158:159], off offset:96
	global_load_dwordx2 v[228:229], v[158:159], off offset:128
	global_load_dwordx2 v[230:231], v[158:159], off offset:160
	global_load_dwordx2 v[232:233], v[158:159], off offset:192
	global_load_dwordx2 v[234:235], v[158:159], off offset:224
	v_mov_b32_e32 v49, v48
	v_mov_b32_e32 v178, v186
	s_mov_b32 s71, s26
	s_mov_b32 s28, s27
	s_waitcnt vmcnt(7)
	v_lshlrev_b32_e32 v54, 16, v220
	v_and_b32_e32 v55, 0xffff0000, v220
	v_lshlrev_b32_e32 v46, 16, v221
	v_and_b32_e32 v47, 0xffff0000, v221
	v_pk_fma_f32 v[50:51], v[50:51], v[56:57], v[54:55]
	v_pk_fma_f32 v[46:47], v[52:53], v[58:59], v[46:47]
	v_cvt_pk_bf16_f32 v50, v50, v51
	v_cvt_pk_bf16_f32 v51, v46, v47

; DI float bflo(unsigned u) { return __uint_as_float(u << 16); }
; DI float bfhi(unsigned u) { return __uint_as_float(u & 0xffff0000u); }
; template <bool FIRST>
; DI void nsa_flush(const int quad, bf16_t* optr, const AttnSt& st, const float (&sc)[2]) {
;     ...
;       uint2* q = (uint2*)(optr + h * 64 + dt * 16 + quad * 4);
;       f32x4 o = st.O[h][dt] * sc[h];
;       if (!FIRST) {
;         uint2 pv = *q;
;         o[0] += bflo(pv.x); o[1] += bfhi(pv.x); o[2] += bflo(pv.y); o[3] += bfhi(pv.y);
;       }
;       uint2 u;
;       u.x = pack2(o[0], o[1]);
;       u.y = pack2(o[2], o[3]);
;       *q = u;
	s_nop 0
	global_store_dwordx2 v[158:159], v[50:51], off
	s_waitcnt vmcnt(7)
	v_lshlrev_b32_e32 v50, 16, v222
	v_and_b32_e32 v51, 0xffff0000, v222
	v_lshlrev_b32_e32 v46, 16, v223
	v_and_b32_e32 v47, 0xffff0000, v223
	v_pk_fma_f32 v[42:43], v[42:43], v[56:57], v[50:51]
	v_pk_fma_f32 v[44:45], v[44:45], v[58:59], v[46:47]
	v_cvt_pk_bf16_f32 v42, v42, v43
	v_cvt_pk_bf16_f32 v43, v44, v45
	global_store_dwordx2 v[158:159], v[42:43], off offset:32

; DI float bflo(unsigned u) { return __uint_as_float(u << 16); }
; DI float bfhi(unsigned u) { return __uint_as_float(u & 0xffff0000u); }
; DI void st_reset(AttnSt& st) {
; #pragma unroll
;   for (int h = 0; h < 2; ++h) {
;     st.m[h] = -1e30f;
;     st.l[h] = 0.f;
;     st.L[h] = f32x4{0.f, 0.f, 0.f, 0.f};
; #pragma unroll
;     for (int dt = 0; dt < 4; ++dt) st.O[h][dt] = f32x4{0.f, 0.f, 0.f, 0.f};
;   }
; template <bool FIRST>
; DI void nsa_flush(const int quad, bf16_t* optr, const AttnSt& st, const float (&sc)[2]) {
;     ...
;       uint2* q = (uint2*)(optr + h * 64 + dt * 16 + quad * 4);
;       f32x4 o = st.O[h][dt] * sc[h];
;       if (!FIRST) {
;         uint2 pv = *q;
;         o[0] += bflo(pv.x); o[1] += bfhi(pv.x); o[2] += bflo(pv.y); o[3] += bfhi(pv.y);
;       }
;       uint2 u;
;       u.x = pack2(o[0], o[1]);
;       u.y = pack2(o[2], o[3]);
;       *q = u;
	v_mov_b32_e32 v46, 0
	v_mov_b32_e32 v47, v46
	v_mov_b32_e32 v54, v46
	v_mov_b32_e32 v55, v46
	v_mov_b32_e32 v50, v46
	v_mov_b32_e32 v51, v46
	v_mov_b32_e32 v52, v46
	v_mov_b32_e32 v53, v46
	s_waitcnt vmcnt(7)
	v_lshlrev_b32_e32 v44, 16, v224
	v_and_b32_e32 v45, 0xffff0000, v224
	v_lshlrev_b32_e32 v42, 16, v225
	v_and_b32_e32 v43, 0xffff0000, v225
	v_pk_fma_f32 v[38:39], v[38:39], v[56:57], v[44:45]
	v_pk_fma_f32 v[40:41], v[40:41], v[58:59], v[42:43]
	v_cvt_pk_bf16_f32 v38, v38, v39
	v_cvt_pk_bf16_f32 v39, v40, v41
	global_store_dwordx2 v[158:159], v[38:39], off offset:64

; DI float bflo(unsigned u) { return __uint_as_float(u << 16); }
; DI float bfhi(unsigned u) { return __uint_as_float(u & 0xffff0000u); }
; DI void st_reset(AttnSt& st) {
; #pragma unroll
;   for (int h = 0; h < 2; ++h) {
;     st.m[h] = -1e30f;
;     st.l[h] = 0.f;
;     st.L[h] = f32x4{0.f, 0.f, 0.f, 0.f};
; #pragma unroll
;     for (int dt = 0; dt < 4; ++dt) st.O[h][dt] = f32x4{0.f, 0.f, 0.f, 0.f};
;   }
; template <bool FIRST>
; DI void nsa_flush(const int quad, bf16_t* optr, const AttnSt& st, const float (&sc)[2]) {
;     ...
;       uint2* q = (uint2*)(optr + h * 64 + dt * 16 + quad * 4);
;       f32x4 o = st.O[h][dt] * sc[h];
;       if (!FIRST) {
;         uint2 pv = *q;
;         o[0] += bflo(pv.x); o[1] += bfhi(pv.x); o[2] += bflo(pv.y); o[3] += bfhi(pv.y);
;       }
;       uint2 u;
;       u.x = pack2(o[0], o[1]);
;       u.y = pack2(o[2], o[3]);
;       *q = u;
	v_mov_b32_e32 v42, v46
	v_mov_b32_e32 v43, v46
	v_mov_b32_e32 v44, v46
	v_mov_b32_e32 v45, v46
	s_waitcnt vmcnt(7)
	v_lshlrev_b32_e32 v40, 16, v226
	v_and_b32_e32 v41, 0xffff0000, v226
	v_lshlrev_b32_e32 v38, 16, v227
	v_and_b32_e32 v39, 0xffff0000, v227
	v_pk_fma_f32 v[34:35], v[34:35], v[56:57], v[40:41]
	v_pk_fma_f32 v[36:37], v[36:37], v[58:59], v[38:39]
	v_cvt_pk_bf16_f32 v34, v34, v35
	v_cvt_pk_bf16_f32 v35, v36, v37

; DI float bflo(unsigned u) { return __uint_as_float(u << 16); }
; DI float bfhi(unsigned u) { return __uint_as_float(u & 0xffff0000u); }
; template <bool FIRST>
; DI void nsa_flush(const int quad, bf16_t* optr, const AttnSt& st, const float (&sc)[2]) {
;     ...
;       uint2* q = (uint2*)(optr + h * 64 + dt * 16 + quad * 4);
;       f32x4 o = st.O[h][dt] * sc[h];
;       if (!FIRST) {
;         uint2 pv = *q;
;         o[0] += bflo(pv.x); o[1] += bfhi(pv.x); o[2] += bflo(pv.y); o[3] += bfhi(pv.y);
;       }
;       uint2 u;
;       u.x = pack2(o[0], o[1]);
;       u.y = pack2(o[2], o[3]);
;       *q = u;
	v_mov_b32_e32 v40, v46
	global_store_dwordx2 v[158:159], v[34:35], off offset:96
	v_mov_b32_e32 v34, v48
	v_mov_b32_e32 v35, v48
	v_mov_b32_e32 v41, v46
	v_mov_b32_e32 v56, v46
	v_mov_b32_e32 v57, v46
	s_waitcnt vmcnt(7)
	v_lshlrev_b32_e32 v38, 16, v228
	v_and_b32_e32 v39, 0xffff0000, v228
	v_lshlrev_b32_e32 v36, 16, v229
	v_and_b32_e32 v37, 0xffff0000, v229
	v_pk_fma_f32 v[30:31], v[30:31], v[34:35], v[38:39]
	v_pk_fma_f32 v[32:33], v[32:33], v[48:49], v[36:37]
	v_cvt_pk_bf16_f32 v30, v30, v31
	v_cvt_pk_bf16_f32 v31, v32, v33
	global_store_dwordx2 v[158:159], v[30:31], off offset:128

; DI float bflo(unsigned u) { return __uint_as_float(u << 16); }
; DI float bfhi(unsigned u) { return __uint_as_float(u & 0xffff0000u); }
; template <bool FIRST>
; DI void nsa_flush(const int quad, bf16_t* optr, const AttnSt& st, const float (&sc)[2]) {
;     ...
;       uint2* q = (uint2*)(optr + h * 64 + dt * 16 + quad * 4);
;       f32x4 o = st.O[h][dt] * sc[h];
;       if (!FIRST) {
;         uint2 pv = *q;
;         o[0] += bflo(pv.x); o[1] += bfhi(pv.x); o[2] += bflo(pv.y); o[3] += bfhi(pv.y);
;       }
;       uint2 u;
;       u.x = pack2(o[0], o[1]);
;       u.y = pack2(o[2], o[3]);
;       *q = u;
	v_mov_b32_e32 v38, v46
	v_mov_b32_e32 v39, v46
	v_mov_b32_e32 v36, v46
	v_mov_b32_e32 v37, v46
	s_waitcnt vmcnt(7)
	v_lshlrev_b32_e32 v32, 16, v230
	v_and_b32_e32 v33, 0xffff0000, v230
	v_lshlrev_b32_e32 v30, 16, v231
	v_and_b32_e32 v31, 0xffff0000, v231
	v_pk_fma_f32 v[26:27], v[26:27], v[34:35], v[32:33]
	v_pk_fma_f32 v[28:29], v[28:29], v[48:49], v[30:31]
	v_cvt_pk_bf16_f32 v26, v26, v27
	v_cvt_pk_bf16_f32 v27, v28, v29
	global_store_dwordx2 v[158:159], v[26:27], off offset:160

; DI float bflo(unsigned u) { return __uint_as_float(u << 16); }
; DI float bfhi(unsigned u) { return __uint_as_float(u & 0xffff0000u); }
; template <bool FIRST>
; DI void nsa_flush(const int quad, bf16_t* optr, const AttnSt& st, const float (&sc)[2]) {
;     ...
;       uint2* q = (uint2*)(optr + h * 64 + dt * 16 + quad * 4);
;       f32x4 o = st.O[h][dt] * sc[h];
;       if (!FIRST) {
;         uint2 pv = *q;
;         o[0] += bflo(pv.x); o[1] += bfhi(pv.x); o[2] += bflo(pv.y); o[3] += bfhi(pv.y);
;       }
;       uint2 u;
;       u.x = pack2(o[0], o[1]);
;       u.y = pack2(o[2], o[3]);
;       *q = u;
	v_mov_b32_e32 v30, v46
	v_mov_b32_e32 v31, v46
	v_mov_b32_e32 v32, v46
	v_mov_b32_e32 v33, v46
	s_waitcnt vmcnt(7)
	v_lshlrev_b32_e32 v28, 16, v232
	v_and_b32_e32 v29, 0xffff0000, v232
	v_lshlrev_b32_e32 v26, 16, v233
	v_and_b32_e32 v27, 0xffff0000, v233
	v_pk_fma_f32 v[22:23], v[22:23], v[34:35], v[28:29]
	v_pk_fma_f32 v[24:25], v[24:25], v[48:49], v[26:27]
	v_cvt_pk_bf16_f32 v22, v22, v23
	v_cvt_pk_bf16_f32 v23, v24, v25
	global_store_dwordx2 v[158:159], v[22:23], off offset:192

; DI float bflo(unsigned u) { return __uint_as_float(u << 16); }
; DI float bfhi(unsigned u) { return __uint_as_float(u & 0xffff0000u); }
; template <bool FIRST>
; DI void nsa_flush(const int quad, bf16_t* optr, const AttnSt& st, const float (&sc)[2]) {
;     ...
;       uint2* q = (uint2*)(optr + h * 64 + dt * 16 + quad * 4);
;       f32x4 o = st.O[h][dt] * sc[h];
;       if (!FIRST) {
;         uint2 pv = *q;
;         o[0] += bflo(pv.x); o[1] += bfhi(pv.x); o[2] += bflo(pv.y); o[3] += bfhi(pv.y);
;       }
;       uint2 u;
;       u.x = pack2(o[0], o[1]);
;       u.y = pack2(o[2], o[3]);
;       *q = u;
; template <bool FX>
; DI void nsa_tile(const Params& p, int b, int g, int tile, bf16_t* lds, const float CL) {
;     ...
;     st_reset(st);
;     {
;       const bf16_t* kb = zb + C_KW + g * 64;
;       const int s0 = (cur >= 8) ? cur - 8 : 0;
;       tile64_gload(tid, rk0, rk1, kb + (size_t)s0 * 64 * ZS, ZS);
;       tile64_gload(tid, rv0, rv1, vwT + s0 * 64, TS);
	v_mov_b32_e32 v26, v46
	v_mov_b32_e32 v27, v46
	v_mov_b32_e32 v28, v46
	v_mov_b32_e32 v29, v46
	s_waitcnt vmcnt(7)
	v_lshlrev_b32_e32 v24, 16, v234
	v_and_b32_e32 v25, 0xffff0000, v234
	v_lshlrev_b32_e32 v22, 16, v235
	v_and_b32_e32 v23, 0xffff0000, v235
	v_pk_fma_f32 v[18:19], v[18:19], v[34:35], v[24:25]
	v_pk_fma_f32 v[20:21], v[20:21], v[48:49], v[22:23]
	v_cvt_pk_bf16_f32 v18, v18, v19
	v_cvt_pk_bf16_f32 v19, v20, v21
	global_store_dwordx2 v[158:159], v[18:19], off offset:224
	s_and_b32 s88, s76, 0xffff3fff
	s_or_b32 s88, s88, 0x4000
	s_movk_i32 s84, 0x800
	s_mov_b32 s85, 0
	v_lshl_add_u64 v[58:59], v[146:147], 0, v[218:219]
	v_lshl_add_u64 v[60:61], v[148:149], 0, v[218:219]
	v_lshl_add_u64 v[62:63], v[150:151], 0, v[218:219]
	v_lshl_add_u64 v[64:65], v[152:153], 0, v[218:219]
	v_lshl_add_u64 v[58:59], v[58:59], 0, s[84:85]
	v_lshl_add_u64 v[60:61], v[60:61], 0, s[84:85]
	s_mov_b32 m0, s88
	s_nop 0
	global_load_lds_dwordx4 v[58:59], off
	s_add_u32 m0, s88, 0x1000
	s_nop 0
	global_load_lds_dwordx4 v[60:61], off
	s_add_u32 m0, s88, 0x2000
	s_nop 0
	global_load_lds_dwordx4 v[62:63], off
	s_add_u32 m0, s88, 0x3000
	s_nop 0
	global_load_lds_dwordx4 v[64:65], off
	s_xor_b32 s88, s88, 0xc000
	v_xor_b32_e32 v188, 0x4000, v188
	v_xor_b32_e32 v189, 0x4000, v189
	v_xor_b32_e32 v190, 0x4000, v190
	v_xor_b32_e32 v191, 0x4000, v191
	v_xor_b32_e32 v207, 0x4000, v207
	v_xor_b32_e32 v208, 0x4000, v208
	v_xor_b32_e32 v209, 0x4000, v209
	v_xor_b32_e32 v210, 0x4000, v210
	v_xor_b32_e32 v211, 0x4000, v211
	v_xor_b32_e32 v212, 0x4000, v212
	v_xor_b32_e32 v213, 0x4000, v213
	v_xor_b32_e32 v214, 0x4000, v214
	s_movk_i32 s89, 0x4000
	v_mov_b32_e32 v48, v46
	v_mov_b32_e32 v49, v46
	v_mov_b32_e32 v34, v46
	v_mov_b32_e32 v35, v46
	v_mov_b32_e32 v22, v46
	v_mov_b32_e32 v23, v46
	v_mov_b32_e32 v24, v46
	v_mov_b32_e32 v25, v46
	v_mov_b32_e32 v18, v46
	v_mov_b32_e32 v19, v46
	v_mov_b32_e32 v20, v46
	v_mov_b32_e32 v21, v46
	s_branch .LBB0_681
